# v118 + accumulator zeroing removed: first K-loop iteration peeled with C=0 MFMAs in the FFN-up and residual K-loops, 64-bit zeroing moves elsewhere
# speedup vs baseline: 1.0168x; 1.0048x over previous
; #define PG8_STAGE(bufoff, gbase, voff) do { _Pragma("unroll") for (int _i = 0; _i < 2; ++_i) \
;         __builtin_amdgcn_global_load_lds((const unsigned*)((const char*)(gbase) + (voff)[_i]), (PG8_LAS unsigned*)(lds + (bufoff) + ldsw + _i * 8192), 16, 0, 0); } while (0)
; #define PG8_WAIT_V(n) asm volatile("s_waitcnt vmcnt(" #n ")" ::: "memory")
; #define PG8_BAR __builtin_amdgcn_s_barrier()
; template <class Epi, class Sched, bool ALIGN_EPI = false, bool SP2 = false>
; __device__ __forceinline__ void gemm_phase(PG8_LAS unsigned char* lds, const Gemm g, const Sched& S, const Epi& E) {
;     ...
; #pragma unroll
;     for (int a = 0; a < 2; ++a)
; #pragma unroll
;         for (int b = 0; b < 2; ++b)
; #pragma unroll
;             for (int m = 0; m < 4; ++m)
; #pragma unroll
;                 for (int n = 0; n < 2; ++n) acc[a][b][m][n] = (f32x4){0.f, 0.f, 0.f, 0.f};
;     ...
;         PG8_STAGE(PG8_SB(1, 0), cB + kstep, voffB); PG8_STAGE(PG8_SA(1, 0), cA + kstep, voffA); PG8_STAGE(PG8_SB(1, 1), cB + hstep + kstep, voffB);
;         PG8_WAIT_V(6); PG8_BAR;
.LBB0_896:
	s_add_u32 s6, s62, 0x17400000
	v_and_b32_e32 v1, 48, v0
	v_lshlrev_b32_e32 v2, 6, v0
	s_movk_i32 s5, 0x3c0
	v_lshlrev_b32_e32 v0, 2, v0
	s_addc_u32 s7, s63, 0
	s_lshl_b32 s42, s2, 6
	s_lshl_b32 s2, s2, 13
	v_and_or_b32 v1, v2, s5, v1
	v_and_b32_e32 v0, 32, v0
	v_bitop3_b32 v2, v1, s2, v0 bitop3:0xde
	s_lshl_b32 s2, s3, 5
	s_and_b32 s50, s2, 0x60
	s_lshl_b32 s2, s50, 7
	v_bitop3_b32 v206, s2, v1, v0 bitop3:0xf6
	s_add_u32 s2, s66, 0x8000
	v_mov_b32_e32 v163, v221
	s_addc_u32 s3, s67, 0
	s_add_i32 m0, s33, 0x18000
	v_lshl_add_u64 v[0:1], s[2:3], 0, v[162:163]
	v_mov_b32_e32 v167, v221
	s_waitcnt vmcnt(2)
	s_barrier
	global_load_lds_dwordx4 v[0:1], off
	s_add_i32 m0, s33, 0x1a000
	v_lshl_add_u64 v[0:1], s[2:3], 0, v[166:167]
	s_add_u32 s2, s18, 0x8000
	v_mov_b32_e32 v161, v221
	s_addc_u32 s3, s19, 0
	s_add_i32 s51, s33, 0x8000
	v_mov_b32_e32 v165, v221
	global_load_lds_dwordx4 v[0:1], off
	s_mov_b32 m0, s51
	s_add_i32 s52, s33, 0xa000
	global_load_lds_dwordx4 v160, s[2:3]
	v_lshl_add_u64 v[0:1], s[2:3], 0, v[164:165]
	s_add_u32 s2, s66, 0xc000
	s_mov_b32 m0, s52
	s_addc_u32 s3, s67, 0
	global_load_lds_dwordx4 v[0:1], off
	s_add_i32 m0, s33, 0x1c000
	s_nop 0
	global_load_lds_dwordx4 v162, s[2:3]
	s_add_i32 m0, s33, 0x1e000
	s_cmpk_lt_u32 s8, 0x100
	global_load_lds_dwordx4 v166, s[2:3]
	s_waitcnt vmcnt(6)
	s_cselect_b64 s[8:9], -1, 0
	s_add_u32 s53, s62, 0xa400a00
	v_mov_b32_e32 v0, 0
	s_addc_u32 s54, s63, 0
	s_ashr_i32 s55, s58, 31
	s_mov_b32 s56, 1
	v_add_u32_e32 v207, 0, v2
	v_mov_b64_e32 v[0:1], 0
	v_mov_b64_e32 v[2:3], 0
	v_mov_b64_e32 v[4:5], 0
	v_mov_b64_e32 v[6:7], 0
	v_mov_b64_e32 v[8:9], 0
	v_mov_b64_e32 v[10:11], 0
	v_mov_b64_e32 v[12:13], 0
	v_mov_b64_e32 v[14:15], 0
	v_mov_b64_e32 v[16:17], 0
	v_mov_b64_e32 v[18:19], 0
	v_mov_b64_e32 v[20:21], 0
	v_mov_b64_e32 v[22:23], 0
	v_mov_b64_e32 v[24:25], 0
	v_mov_b64_e32 v[26:27], 0
	v_mov_b64_e32 v[28:29], 0
	v_mov_b64_e32 v[30:31], 0
	v_mov_b64_e32 v[32:33], 0
	v_mov_b64_e32 v[34:35], 0
	v_mov_b64_e32 v[36:37], 0
	v_mov_b64_e32 v[38:39], 0
	v_mov_b64_e32 v[40:41], 0
	v_mov_b64_e32 v[42:43], 0
	v_mov_b64_e32 v[44:45], 0
	v_mov_b64_e32 v[46:47], 0
	v_mov_b64_e32 v[48:49], 0
	v_mov_b64_e32 v[50:51], 0
	v_mov_b64_e32 v[52:53], 0
	v_mov_b64_e32 v[54:55], 0
	v_mov_b64_e32 v[56:57], 0
	v_mov_b64_e32 v[58:59], 0
	v_mov_b64_e32 v[60:61], 0
	v_mov_b64_e32 v[62:63], 0
	v_mov_b64_e32 v[64:65], 0
	v_mov_b64_e32 v[66:67], 0
	v_mov_b64_e32 v[68:69], 0
	v_mov_b64_e32 v[70:71], 0
	v_mov_b64_e32 v[72:73], 0
	v_mov_b64_e32 v[74:75], 0
	v_mov_b64_e32 v[76:77], 0
	v_mov_b64_e32 v[78:79], 0
	v_mov_b64_e32 v[80:81], 0
	v_mov_b64_e32 v[82:83], 0
	v_mov_b64_e32 v[84:85], 0
	v_mov_b64_e32 v[86:87], 0
	v_mov_b64_e32 v[88:89], 0
	v_mov_b64_e32 v[90:91], 0
	v_mov_b64_e32 v[92:93], 0
	v_mov_b64_e32 v[94:95], 0
	v_mov_b64_e32 v[96:97], 0
	v_mov_b64_e32 v[98:99], 0
	v_mov_b64_e32 v[100:101], 0
	v_mov_b64_e32 v[102:103], 0
	v_mov_b64_e32 v[104:105], 0
	v_mov_b64_e32 v[106:107], 0
	v_mov_b64_e32 v[108:109], 0
	v_mov_b64_e32 v[110:111], 0
	v_mov_b64_e32 v[112:113], 0
	v_mov_b64_e32 v[114:115], 0
	v_mov_b64_e32 v[116:117], 0
	v_mov_b64_e32 v[118:119], 0
	v_mov_b64_e32 v[120:121], 0
	v_mov_b64_e32 v[122:123], 0
	v_mov_b64_e32 v[124:125], 0
	v_mov_b64_e32 v[126:127], 0
	s_barrier
	s_branch .LBB0_899

; template <class Epi, class Sched, bool ALIGN_EPI = false, bool SP2 = false>
; __device__ __forceinline__ void gemm_phase(PG8_LAS unsigned char* lds, const Gemm g, const Sched& S, const Epi& E) {
;     ...
;         if (!has_next) break;
;         if (!keep)
; #pragma unroll
;         for (int a = 0; a < 2; ++a)
; #pragma unroll
;             for (int b = 0; b < 2; ++b)
; #pragma unroll
;                 for (int m = 0; m < 4; ++m)
; #pragma unroll
;                     for (int n = 0; n < 2; ++n) acc[a][b][m][n] = (f32x4){0.f, 0.f, 0.f, 0.f};
.LBB0_945:
	s_andn2_b64 vcc, exec, s[2:3]
	s_mov_b64 s[2:3], -1
	s_cbranch_vccnz .LBB0_898
	s_andn2_b64 vcc, exec, s[18:19]
	s_cbranch_vccnz .LBB0_948
	v_mov_b32_e32 v0, 0
	v_mov_b64_e32 v[0:1], 0
	v_mov_b64_e32 v[2:3], 0
	v_mov_b64_e32 v[4:5], 0
	v_mov_b64_e32 v[6:7], 0
	v_mov_b64_e32 v[8:9], 0
	v_mov_b64_e32 v[10:11], 0
	v_mov_b64_e32 v[12:13], 0
	v_mov_b64_e32 v[14:15], 0
	v_mov_b64_e32 v[16:17], 0
	v_mov_b64_e32 v[18:19], 0
	v_mov_b64_e32 v[20:21], 0
	v_mov_b64_e32 v[22:23], 0
	v_mov_b64_e32 v[24:25], 0
	v_mov_b64_e32 v[26:27], 0
	v_mov_b64_e32 v[28:29], 0
	v_mov_b64_e32 v[30:31], 0
	v_mov_b64_e32 v[32:33], 0
	v_mov_b64_e32 v[34:35], 0
	v_mov_b64_e32 v[36:37], 0
	v_mov_b64_e32 v[38:39], 0
	v_mov_b64_e32 v[40:41], 0
	v_mov_b64_e32 v[42:43], 0
	v_mov_b64_e32 v[44:45], 0
	v_mov_b64_e32 v[46:47], 0
	v_mov_b64_e32 v[48:49], 0
	v_mov_b64_e32 v[50:51], 0
	v_mov_b64_e32 v[52:53], 0
	v_mov_b64_e32 v[54:55], 0
	v_mov_b64_e32 v[56:57], 0
	v_mov_b64_e32 v[58:59], 0
	v_mov_b64_e32 v[60:61], 0
	v_mov_b64_e32 v[62:63], 0
	v_mov_b64_e32 v[64:65], 0
	v_mov_b64_e32 v[66:67], 0
	v_mov_b64_e32 v[68:69], 0
	v_mov_b64_e32 v[70:71], 0
	v_mov_b64_e32 v[72:73], 0
	v_mov_b64_e32 v[74:75], 0
	v_mov_b64_e32 v[76:77], 0
	v_mov_b64_e32 v[78:79], 0
	v_mov_b64_e32 v[80:81], 0
	v_mov_b64_e32 v[82:83], 0
	v_mov_b64_e32 v[84:85], 0
	v_mov_b64_e32 v[86:87], 0
	v_mov_b64_e32 v[88:89], 0
	v_mov_b64_e32 v[90:91], 0
	v_mov_b64_e32 v[92:93], 0
	v_mov_b64_e32 v[94:95], 0
	v_mov_b64_e32 v[96:97], 0
	v_mov_b64_e32 v[98:99], 0
	v_mov_b64_e32 v[100:101], 0
	v_mov_b64_e32 v[102:103], 0
	v_mov_b64_e32 v[104:105], 0
	v_mov_b64_e32 v[106:107], 0
	v_mov_b64_e32 v[108:109], 0
	v_mov_b64_e32 v[110:111], 0
	v_mov_b64_e32 v[112:113], 0
	v_mov_b64_e32 v[114:115], 0
	v_mov_b64_e32 v[116:117], 0
	v_mov_b64_e32 v[118:119], 0
	v_mov_b64_e32 v[120:121], 0
	v_mov_b64_e32 v[122:123], 0
	v_mov_b64_e32 v[124:125], 0
	v_mov_b64_e32 v[126:127], 0

;     __device__ bool next(int i, Unit& u) const { Unit t; if (!base.next(i >> 2, t)) return false; const int br = i & 3; u.pm = br * 64 + t.pm; u.pn = br * 4 + t.pn; return true; }
; template <class Epi, class Sched, bool ALIGN_EPI = false, bool SP2 = false>
; __device__ __forceinline__ void gemm_phase(PG8_LAS unsigned char* lds, const Gemm g, const Sched& S, const Epi& E) {
;     ...
; #pragma unroll
;     for (int a = 0; a < 2; ++a)
; #pragma unroll
;         for (int b = 0; b < 2; ++b)
; #pragma unroll
;             for (int m = 0; m < 4; ++m)
; #pragma unroll
;                 for (int n = 0; n < 2; ++n) acc[a][b][m][n] = (f32x4){0.f, 0.f, 0.f, 0.f};
;     ...
;         const bool has_next = S.next(ui + 1, nxt);
;         const char* nA = has_next ? (const char*)g.A + (size_t)nxt.pm * tstep : cA; const char* nB = has_next ? (const char*)g.Bt + (size_t)nxt.pn * tstep : cB;
.LBB0_1129:
	s_ashr_i32 s79, s78, 31
	s_lshl_b64 s[22:23], s[78:79], 19
	v_readlane_b32 s5, v255, 15
	s_add_u32 s80, s5, s22
	s_addc_u32 s81, s61, s23
	s_and_b64 s[22:23], s[2:3], exec
	s_cselect_b32 s5, s81, s7
	s_cselect_b32 s9, s80, s6
	s_ashr_i32 s77, s76, 31
	s_lshl_b64 s[22:23], s[76:77], 19
	s_add_u32 s82, s55, s22
	s_addc_u32 s83, s56, s23
	s_and_b64 s[22:23], s[2:3], exec
	s_cselect_b32 s22, s83, s11
	s_cselect_b32 s23, s82, s10
	s_add_u32 s6, s6, 0xc000
	s_addc_u32 s7, s7, 0
	s_add_u32 s30, s10, 0x10000
	v_mov_b32_e32 v0, 0
	s_addc_u32 s37, s11, 0
	s_mov_b32 s40, -2
	v_mov_b64_e32 v[0:1], 0
	v_mov_b64_e32 v[2:3], 0
	v_mov_b64_e32 v[4:5], 0
	v_mov_b64_e32 v[6:7], 0
	v_mov_b64_e32 v[8:9], 0
	v_mov_b64_e32 v[10:11], 0
	v_mov_b64_e32 v[12:13], 0
	v_mov_b64_e32 v[14:15], 0
	v_mov_b64_e32 v[28:29], 0
	v_mov_b64_e32 v[30:31], 0
	v_mov_b64_e32 v[36:37], 0
	v_mov_b64_e32 v[38:39], 0
	v_mov_b64_e32 v[40:41], 0
	v_mov_b64_e32 v[42:43], 0
	v_mov_b64_e32 v[44:45], 0
	v_mov_b64_e32 v[46:47], 0
	v_mov_b64_e32 v[64:65], 0
	v_mov_b64_e32 v[66:67], 0
	v_mov_b64_e32 v[68:69], 0
	v_mov_b64_e32 v[70:71], 0
	v_mov_b64_e32 v[72:73], 0
	v_mov_b64_e32 v[74:75], 0
	v_mov_b64_e32 v[76:77], 0
	v_mov_b64_e32 v[78:79], 0
	v_mov_b64_e32 v[80:81], 0
	v_mov_b64_e32 v[82:83], 0
	v_mov_b64_e32 v[84:85], 0
	v_mov_b64_e32 v[86:87], 0
	v_mov_b64_e32 v[88:89], 0
	v_mov_b64_e32 v[90:91], 0
	v_mov_b64_e32 v[92:93], 0
	v_mov_b64_e32 v[94:95], 0
	v_mov_b64_e32 v[96:97], 0
	v_mov_b64_e32 v[98:99], 0
	v_mov_b64_e32 v[100:101], 0
	v_mov_b64_e32 v[102:103], 0
	v_mov_b64_e32 v[104:105], 0
	v_mov_b64_e32 v[106:107], 0
	v_mov_b64_e32 v[108:109], 0
	v_mov_b64_e32 v[110:111], 0
	v_mov_b64_e32 v[112:113], 0
	v_mov_b64_e32 v[114:115], 0
	v_mov_b64_e32 v[116:117], 0
	v_mov_b64_e32 v[118:119], 0
	v_mov_b64_e32 v[120:121], 0
	v_mov_b64_e32 v[122:123], 0
	v_mov_b64_e32 v[124:125], 0
	v_mov_b64_e32 v[126:127], 0
	v_mov_b64_e32 v[128:129], 0
	v_mov_b64_e32 v[130:131], 0
	v_mov_b64_e32 v[132:133], 0
	v_mov_b64_e32 v[134:135], 0
	v_mov_b64_e32 v[136:137], 0
	v_mov_b64_e32 v[138:139], 0
	v_mov_b64_e32 v[140:141], 0
	v_mov_b64_e32 v[142:143], 0
	v_mov_b64_e32 v[144:145], 0
	v_mov_b64_e32 v[146:147], 0
	v_mov_b64_e32 v[148:149], 0
	v_mov_b64_e32 v[150:151], 0
	v_mov_b64_e32 v[152:153], 0
	v_mov_b64_e32 v[154:155], 0
	v_mov_b64_e32 v[156:157], 0
	v_mov_b64_e32 v[158:159], 0
	v_add_u32_e32 v246, 0x10000, v192

; #define PG8_STAGE(bufoff, gbase, voff) do { _Pragma("unroll") for (int _i = 0; _i < 2; ++_i) \
;         __builtin_amdgcn_global_load_lds((const unsigned*)((const char*)(gbase) + (voff)[_i]), (PG8_LAS unsigned*)(lds + (bufoff) + ldsw + _i * 8192), 16, 0, 0); } while (0)
; #define PG8_LDA(dst, b, h) do { _Pragma("unroll") for (int m = 0; m < 4; ++m) _Pragma("unroll") for (int k = 0; k < 2; ++k) dst[m][k] = *(const PG8_LAS bf16x8*)(lds + PG8_SA(b, h) + aoff + m * 2048 + k * 1024); } while (0)
; #define PG8_LDB(dst, b, h) do { _Pragma("unroll") for (int n = 0; n < 2; ++n) _Pragma("unroll") for (int k = 0; k < 2; ++k) dst[n][k] = *(const PG8_LAS bf16x8*)(lds + PG8_SB(b, h) + boff + n * 2048 + k * 1024); } while (0)
; #define PG8_MMA(ai, bj, At, Bt) do { __builtin_amdgcn_s_setprio(1); _Pragma("unroll") for (int m = 0; m < 4; ++m) _Pragma("unroll") for (int n = 0; n < 2; ++n) _Pragma("unroll") for (int k = 0; k < 2; ++k) \
;         acc[ai][bj][m][n] = __builtin_amdgcn_mfma_f32_16x16x32_bf16(Bt[n][k], At[m][k], acc[ai][bj][m][n], 0, 0, 0); __builtin_amdgcn_s_setprio(0); } while (0)
; #define PG8_WAIT_V(n) asm volatile("s_waitcnt vmcnt(" #n ")" ::: "memory")
; #define PG8_WAIT_L(n) asm volatile("s_waitcnt lgkmcnt(" #n ")" ::: "memory")
; #define PG8_BAR __builtin_amdgcn_s_barrier()
; #define PG8_SCHED __builtin_amdgcn_sched_barrier(0)
; template <class Epi, class Sched, bool ALIGN_EPI = false, bool SP2 = false>
; __device__ __forceinline__ void gemm_phase(PG8_LAS unsigned char* lds, const Gemm g, const Sched& S, const Epi& E) {
;     ...
;             PG8_LDB(B0, 0, 0); PG8_LDB(B1, 0, 1); PG8_SCHED; PG8_LDA(At, 0, 0); PG8_STAGE(PG8_SA(1, 1), a1 + hstep, voffA);
;             PG8_WAIT_V(8); PG8_WAIT_L(0); PG8_BAR; PG8_MMA(0, 0, At, B0); PG8_MMA(0, 1, At, B1); PG8_BAR; PG8_SCHED;
;             PG8_LDA(At, 0, 1); PG8_STAGE(PG8_SB(0, 0), b2, voffB); PG8_STAGE(PG8_SB(0, 1), b2 + hstep, voffB); PG8_STAGE(PG8_SA(0, 0), a2, voffA);
;             PG8_WAIT_V(8); PG8_WAIT_L(0); PG8_BAR; PG8_MMA(1, 0, At, B0); PG8_MMA(1, 1, At, B1); PG8_BAR; PG8_SCHED;
.LBB0_1321:
	s_add_u32 s16, s16, 0xc000
	s_addc_u32 s17, s17, 0
	s_add_u32 s66, s18, 0x10000
	v_mov_b32_e32 v0, 0
	s_addc_u32 s67, s19, 0
	s_mov_b32 s18, 0
	v_add_u32_e32 v246, 0x10000, v206
	s_add_i32 s75, s18, 2
	s_add_u32 s19, s16, 0x4000
	s_addc_u32 s20, s17, 0
	s_cmp_eq_u32 s59, s18
	s_cselect_b32 s64, s0, s19
	s_cselect_b32 s65, s1, s20
	s_cselect_b32 s20, s14, s66
	s_cselect_b32 s21, s15, s67
	s_add_u32 s18, s64, 0x8000
	s_addc_u32 s19, s65, 0
	s_add_i32 s76, 0, 0x10000
	s_add_i32 s78, 0, 0x14000
	ds_read_b128 v[80:83], v246
	ds_read_b128 v[84:87], v246 offset:1024
	ds_read_b128 v[104:107], v246 offset:2048
	ds_read_b128 v[108:111], v246 offset:3072
	ds_read_b128 v[128:131], v246 offset:16384
	ds_read_b128 v[136:139], v246 offset:17408
	ds_read_b128 v[152:155], v246 offset:18432
	ds_read_b128 v[156:159], v246 offset:19456
	s_add_i32 m0, s41, 0xc000
	ds_read_b128 v[160:163], v207
	ds_read_b128 v[164:167], v207 offset:1024
	ds_read_b128 v[168:171], v207 offset:2048
	ds_read_b128 v[172:175], v207 offset:3072
	ds_read_b128 v[176:179], v207 offset:4096
	ds_read_b128 v[180:183], v207 offset:5120
	ds_read_b128 v[198:201], v207 offset:6144
	ds_read_b128 v[202:205], v207 offset:7168
	global_load_lds_dwordx4 v194, s[16:17]
	s_add_i32 m0, s41, 0xe000
	s_nop 0
	global_load_lds_dwordx4 v196, s[16:17]
	s_waitcnt vmcnt(8) lgkmcnt(0)
	s_barrier
	v_mfma_f32_16x16x32_bf16 v[148:151], v[80:83], v[160:163], 0
	v_mfma_f32_16x16x32_bf16 v[144:147], v[104:107], v[160:163], 0
	v_mfma_f32_16x16x32_bf16 v[124:127], v[80:83], v[168:171], 0
	v_mfma_f32_16x16x32_bf16 v[120:123], v[104:107], v[168:171], 0
	v_mfma_f32_16x16x32_bf16 v[100:103], v[80:83], v[176:179], 0
	v_mfma_f32_16x16x32_bf16 v[96:99], v[104:107], v[176:179], 0
	v_mfma_f32_16x16x32_bf16 v[76:79], v[80:83], v[198:201], 0
	v_mfma_f32_16x16x32_bf16 v[72:75], v[104:107], v[198:201], 0
	v_mfma_f32_16x16x32_bf16 v[148:151], v[84:87], v[164:167], v[148:151]
	v_mfma_f32_16x16x32_bf16 v[144:147], v[108:111], v[164:167], v[144:147]
	v_mfma_f32_16x16x32_bf16 v[124:127], v[84:87], v[172:175], v[124:127]
	v_mfma_f32_16x16x32_bf16 v[120:123], v[108:111], v[172:175], v[120:123]
	v_mfma_f32_16x16x32_bf16 v[100:103], v[84:87], v[180:183], v[100:103]
	v_mfma_f32_16x16x32_bf16 v[96:99], v[108:111], v[180:183], v[96:99]
	v_mfma_f32_16x16x32_bf16 v[76:79], v[84:87], v[202:205], v[76:79]
	v_mfma_f32_16x16x32_bf16 v[72:75], v[108:111], v[202:205], v[72:75]
	v_mfma_f32_16x16x32_bf16 v[140:143], v[128:131], v[160:163], 0
	v_mfma_f32_16x16x32_bf16 v[132:135], v[152:155], v[160:163], 0
	v_mfma_f32_16x16x32_bf16 v[116:119], v[128:131], v[168:171], 0
	v_mfma_f32_16x16x32_bf16 v[112:115], v[152:155], v[168:171], 0
	v_mfma_f32_16x16x32_bf16 v[92:95], v[128:131], v[176:179], 0
	v_mfma_f32_16x16x32_bf16 v[88:91], v[152:155], v[176:179], 0
	v_mfma_f32_16x16x32_bf16 v[68:71], v[128:131], v[198:201], 0
	v_mfma_f32_16x16x32_bf16 v[64:67], v[152:155], v[198:201], 0
	v_mfma_f32_16x16x32_bf16 v[140:143], v[136:139], v[164:167], v[140:143]
	v_mfma_f32_16x16x32_bf16 v[132:135], v[156:159], v[164:167], v[132:135]
	v_mfma_f32_16x16x32_bf16 v[116:119], v[136:139], v[172:175], v[116:119]
	v_mfma_f32_16x16x32_bf16 v[112:115], v[156:159], v[172:175], v[112:115]
	v_mfma_f32_16x16x32_bf16 v[92:95], v[136:139], v[180:183], v[92:95]
	v_mfma_f32_16x16x32_bf16 v[88:91], v[156:159], v[180:183], v[88:91]
	v_mfma_f32_16x16x32_bf16 v[68:71], v[136:139], v[202:205], v[68:71]
	v_mfma_f32_16x16x32_bf16 v[64:67], v[156:159], v[202:205], v[64:67]
	s_barrier
	s_add_i32 s76, s76, s39
	s_mov_b32 m0, s76
	ds_read_b128 v[160:163], v207 offset:16384
	ds_read_b128 v[164:167], v207 offset:17408
	ds_read_b128 v[168:171], v207 offset:18432
	ds_read_b128 v[172:175], v207 offset:19456
	ds_read_b128 v[176:179], v207 offset:20480
	ds_read_b128 v[180:183], v207 offset:21504
	ds_read_b128 v[198:201], v207 offset:22528
	ds_read_b128 v[202:205], v207 offset:23552
	global_load_lds_dwordx4 v186, s[20:21]
	s_add_i32 m0, s76, 0x2000
	s_add_u32 s76, s20, 0x4000
	s_addc_u32 s77, s21, 0
	s_add_i32 s78, s78, s39
	global_load_lds_dwordx4 v190, s[20:21]
	s_mov_b32 m0, s78
	s_nop 0
	global_load_lds_dwordx4 v186, s[76:77]
	s_add_i32 m0, s78, 0x2000
	s_nop 0
	global_load_lds_dwordx4 v190, s[76:77]
	s_mov_b32 m0, s41
	s_nop 0
	global_load_lds_dwordx4 v184, s[64:65]
	s_mov_b32 m0, s42
	s_nop 0
	global_load_lds_dwordx4 v188, s[64:65]
	s_waitcnt vmcnt(8) lgkmcnt(0)
	s_barrier
	v_mfma_f32_16x16x32_bf16 v[60:63], v[80:83], v[160:163], 0
	v_mfma_f32_16x16x32_bf16 v[56:59], v[104:107], v[160:163], 0
	v_mfma_f32_16x16x32_bf16 v[44:47], v[80:83], v[168:171], 0
	v_mfma_f32_16x16x32_bf16 v[40:43], v[104:107], v[168:171], 0
	v_mfma_f32_16x16x32_bf16 v[28:31], v[80:83], v[176:179], 0
	v_mfma_f32_16x16x32_bf16 v[24:27], v[104:107], v[176:179], 0
	v_mfma_f32_16x16x32_bf16 v[12:15], v[80:83], v[198:201], 0
	v_mfma_f32_16x16x32_bf16 v[8:11], v[104:107], v[198:201], 0
	v_mfma_f32_16x16x32_bf16 v[60:63], v[84:87], v[164:167], v[60:63]
	v_mfma_f32_16x16x32_bf16 v[56:59], v[108:111], v[164:167], v[56:59]
	v_mfma_f32_16x16x32_bf16 v[44:47], v[84:87], v[172:175], v[44:47]
	v_mfma_f32_16x16x32_bf16 v[40:43], v[108:111], v[172:175], v[40:43]
	v_mfma_f32_16x16x32_bf16 v[28:31], v[84:87], v[180:183], v[28:31]
	v_mfma_f32_16x16x32_bf16 v[24:27], v[108:111], v[180:183], v[24:27]
	v_mfma_f32_16x16x32_bf16 v[12:15], v[84:87], v[202:205], v[12:15]
	v_mfma_f32_16x16x32_bf16 v[8:11], v[108:111], v[202:205], v[8:11]
	v_mfma_f32_16x16x32_bf16 v[52:55], v[128:131], v[160:163], 0
	v_mfma_f32_16x16x32_bf16 v[48:51], v[152:155], v[160:163], 0
	v_mfma_f32_16x16x32_bf16 v[36:39], v[128:131], v[168:171], 0
	v_mfma_f32_16x16x32_bf16 v[32:35], v[152:155], v[168:171], 0
	v_mfma_f32_16x16x32_bf16 v[20:23], v[128:131], v[176:179], 0
	v_mfma_f32_16x16x32_bf16 v[16:19], v[152:155], v[176:179], 0
	v_mfma_f32_16x16x32_bf16 v[4:7], v[128:131], v[198:201], 0
	v_mfma_f32_16x16x32_bf16 v[0:3], v[152:155], v[198:201], 0
	v_mfma_f32_16x16x32_bf16 v[52:55], v[136:139], v[164:167], v[52:55]
	v_mfma_f32_16x16x32_bf16 v[48:51], v[156:159], v[164:167], v[48:51]
	v_mfma_f32_16x16x32_bf16 v[36:39], v[136:139], v[172:175], v[36:39]
	v_mfma_f32_16x16x32_bf16 v[32:35], v[156:159], v[172:175], v[32:35]
	v_mfma_f32_16x16x32_bf16 v[20:23], v[136:139], v[180:183], v[20:23]
	v_mfma_f32_16x16x32_bf16 v[16:19], v[156:159], v[180:183], v[16:19]
	v_mfma_f32_16x16x32_bf16 v[4:7], v[136:139], v[202:205], v[4:7]
	v_mfma_f32_16x16x32_bf16 v[0:3], v[156:159], v[202:205], v[0:3]
	s_barrier
; #define PG8_STAGE(bufoff, gbase, voff) do { _Pragma("unroll") for (int _i = 0; _i < 2; ++_i) \
;         __builtin_amdgcn_global_load_lds((const unsigned*)((const char*)(gbase) + (voff)[_i]), (PG8_LAS unsigned*)(lds + (bufoff) + ldsw + _i * 8192), 16, 0, 0); } while (0)
; #define PG8_LDA(dst, b, h) do { _Pragma("unroll") for (int m = 0; m < 4; ++m) _Pragma("unroll") for (int k = 0; k < 2; ++k) dst[m][k] = *(const PG8_LAS bf16x8*)(lds + PG8_SA(b, h) + aoff + m * 2048 + k * 1024); } while (0)
; #define PG8_LDB(dst, b, h) do { _Pragma("unroll") for (int n = 0; n < 2; ++n) _Pragma("unroll") for (int k = 0; k < 2; ++k) dst[n][k] = *(const PG8_LAS bf16x8*)(lds + PG8_SB(b, h) + boff + n * 2048 + k * 1024); } while (0)
; #define PG8_MMA(ai, bj, At, Bt) do { __builtin_amdgcn_s_setprio(1); _Pragma("unroll") for (int m = 0; m < 4; ++m) _Pragma("unroll") for (int n = 0; n < 2; ++n) _Pragma("unroll") for (int k = 0; k < 2; ++k) \
;         acc[ai][bj][m][n] = __builtin_amdgcn_mfma_f32_16x16x32_bf16(Bt[n][k], At[m][k], acc[ai][bj][m][n], 0, 0, 0); __builtin_amdgcn_s_setprio(0); } while (0)
; #define PG8_WAIT_V(n) asm volatile("s_waitcnt vmcnt(" #n ")" ::: "memory")
; #define PG8_WAIT_L(n) asm volatile("s_waitcnt lgkmcnt(" #n ")" ::: "memory")
; #define PG8_BAR __builtin_amdgcn_s_barrier()
; #define PG8_SCHED __builtin_amdgcn_sched_barrier(0)
; template <class Epi, class Sched, bool ALIGN_EPI = false, bool SP2 = false>
; __device__ __forceinline__ void gemm_phase(PG8_LAS unsigned char* lds, const Gemm g, const Sched& S, const Epi& E) {
;     ...
;             PG8_LDB(B0, 1, 0); PG8_LDB(B1, 1, 1); PG8_SCHED; PG8_LDA(At, 1, 0); PG8_STAGE(PG8_SA(0, 1), a2 + hstep, voffA);
;             PG8_WAIT_V(8); PG8_WAIT_L(0); PG8_BAR; PG8_MMA(0, 0, At, B0); PG8_MMA(0, 1, At, B1); PG8_BAR; PG8_SCHED;
;             PG8_LDA(At, 1, 1); PG8_STAGE(PG8_SB(1, 0), b3, voffB); PG8_STAGE(PG8_SB(1, 1), b3 + hstep, voffB); PG8_STAGE(PG8_SA(1, 0), a3, voffA);
;             PG8_WAIT_V(8); PG8_WAIT_L(0); PG8_BAR; PG8_MMA(1, 0, At, B0); PG8_MMA(1, 1, At, B1); PG8_BAR; PG8_SCHED;
	s_add_i32 s76, 0, 0x18000
	s_add_i32 s77, 0, 0x1c000
	ds_read_b128 v[80:83], v246 offset:32768
	ds_read_b128 v[84:87], v246 offset:33792
	ds_read_b128 v[104:107], v246 offset:34816
	ds_read_b128 v[108:111], v246 offset:35840
	ds_read_b128 v[128:131], v246 offset:49152
	ds_read_b128 v[136:139], v246 offset:50176
	ds_read_b128 v[152:155], v246 offset:51200
	ds_read_b128 v[156:159], v246 offset:52224
	s_add_u32 s64, s64, 0x4000
	s_addc_u32 s65, s65, 0
	s_mov_b32 m0, s50
	ds_read_b128 v[160:163], v207 offset:32768
	ds_read_b128 v[164:167], v207 offset:33792
	ds_read_b128 v[168:171], v207 offset:34816
	ds_read_b128 v[172:175], v207 offset:35840
	ds_read_b128 v[176:179], v207 offset:36864
	ds_read_b128 v[180:183], v207 offset:37888
	ds_read_b128 v[198:201], v207 offset:38912
	ds_read_b128 v[202:205], v207 offset:39936
	global_load_lds_dwordx4 v184, s[64:65]
	s_mov_b32 m0, s51
	s_nop 0
	global_load_lds_dwordx4 v188, s[64:65]
	s_waitcnt vmcnt(8) lgkmcnt(0)
	s_barrier
	v_mfma_f32_16x16x32_bf16 v[148:151], v[80:83], v[160:163], v[148:151]
	v_mfma_f32_16x16x32_bf16 v[144:147], v[104:107], v[160:163], v[144:147]
	v_mfma_f32_16x16x32_bf16 v[124:127], v[80:83], v[168:171], v[124:127]
	v_mfma_f32_16x16x32_bf16 v[120:123], v[104:107], v[168:171], v[120:123]
	v_mfma_f32_16x16x32_bf16 v[100:103], v[80:83], v[176:179], v[100:103]
	v_mfma_f32_16x16x32_bf16 v[96:99], v[104:107], v[176:179], v[96:99]
	v_mfma_f32_16x16x32_bf16 v[76:79], v[80:83], v[198:201], v[76:79]
	v_mfma_f32_16x16x32_bf16 v[72:75], v[104:107], v[198:201], v[72:75]
	v_mfma_f32_16x16x32_bf16 v[148:151], v[84:87], v[164:167], v[148:151]
	v_mfma_f32_16x16x32_bf16 v[144:147], v[108:111], v[164:167], v[144:147]
	v_mfma_f32_16x16x32_bf16 v[124:127], v[84:87], v[172:175], v[124:127]
	v_mfma_f32_16x16x32_bf16 v[120:123], v[108:111], v[172:175], v[120:123]
	v_mfma_f32_16x16x32_bf16 v[100:103], v[84:87], v[180:183], v[100:103]
	v_mfma_f32_16x16x32_bf16 v[96:99], v[108:111], v[180:183], v[96:99]
	v_mfma_f32_16x16x32_bf16 v[76:79], v[84:87], v[202:205], v[76:79]
	v_mfma_f32_16x16x32_bf16 v[72:75], v[108:111], v[202:205], v[72:75]
	v_mfma_f32_16x16x32_bf16 v[140:143], v[128:131], v[160:163], v[140:143]
	v_mfma_f32_16x16x32_bf16 v[132:135], v[152:155], v[160:163], v[132:135]
	v_mfma_f32_16x16x32_bf16 v[116:119], v[128:131], v[168:171], v[116:119]
	v_mfma_f32_16x16x32_bf16 v[112:115], v[152:155], v[168:171], v[112:115]
	v_mfma_f32_16x16x32_bf16 v[92:95], v[128:131], v[176:179], v[92:95]
	v_mfma_f32_16x16x32_bf16 v[88:91], v[152:155], v[176:179], v[88:91]
	v_mfma_f32_16x16x32_bf16 v[68:71], v[128:131], v[198:201], v[68:71]
	v_mfma_f32_16x16x32_bf16 v[64:67], v[152:155], v[198:201], v[64:67]
	v_mfma_f32_16x16x32_bf16 v[140:143], v[136:139], v[164:167], v[140:143]
	v_mfma_f32_16x16x32_bf16 v[132:135], v[156:159], v[164:167], v[132:135]
	v_mfma_f32_16x16x32_bf16 v[116:119], v[136:139], v[172:175], v[116:119]
	v_mfma_f32_16x16x32_bf16 v[112:115], v[156:159], v[172:175], v[112:115]
	v_mfma_f32_16x16x32_bf16 v[92:95], v[136:139], v[180:183], v[92:95]
	v_mfma_f32_16x16x32_bf16 v[88:91], v[156:159], v[180:183], v[88:91]
	v_mfma_f32_16x16x32_bf16 v[68:71], v[136:139], v[202:205], v[68:71]
	v_mfma_f32_16x16x32_bf16 v[64:67], v[156:159], v[202:205], v[64:67]
	s_barrier
	s_add_u32 s64, s20, 0x8000
	s_addc_u32 s65, s21, 0
	s_add_i32 s76, s76, s39
	s_mov_b32 m0, s76
	ds_read_b128 v[160:163], v207 offset:49152
	ds_read_b128 v[164:167], v207 offset:50176
	ds_read_b128 v[168:171], v207 offset:51200
	ds_read_b128 v[172:175], v207 offset:52224
	ds_read_b128 v[176:179], v207 offset:53248
	ds_read_b128 v[180:183], v207 offset:54272
	ds_read_b128 v[198:201], v207 offset:55296
	ds_read_b128 v[202:205], v207 offset:56320
	global_load_lds_dwordx4 v186, s[64:65]
	s_add_i32 m0, s76, 0x2000
	s_add_u32 s20, s20, 0xc000
	s_addc_u32 s21, s21, 0
	s_add_i32 s91, s77, s39
	global_load_lds_dwordx4 v190, s[64:65]
	s_mov_b32 m0, s91
	s_nop 0
	global_load_lds_dwordx4 v186, s[20:21]
	s_add_i32 m0, s91, 0x2000
	s_nop 0
	global_load_lds_dwordx4 v190, s[20:21]
	s_mov_b32 m0, s56
	s_nop 0
	global_load_lds_dwordx4 v184, s[18:19]
	s_mov_b32 m0, s57
	s_nop 0
	global_load_lds_dwordx4 v188, s[18:19]
	s_waitcnt vmcnt(8) lgkmcnt(0)
	s_barrier
	v_mfma_f32_16x16x32_bf16 v[60:63], v[80:83], v[160:163], v[60:63]
	v_mfma_f32_16x16x32_bf16 v[56:59], v[104:107], v[160:163], v[56:59]
	v_mfma_f32_16x16x32_bf16 v[44:47], v[80:83], v[168:171], v[44:47]
	v_mfma_f32_16x16x32_bf16 v[40:43], v[104:107], v[168:171], v[40:43]
	v_mfma_f32_16x16x32_bf16 v[28:31], v[80:83], v[176:179], v[28:31]
	v_mfma_f32_16x16x32_bf16 v[24:27], v[104:107], v[176:179], v[24:27]
	v_mfma_f32_16x16x32_bf16 v[12:15], v[80:83], v[198:201], v[12:15]
	v_mfma_f32_16x16x32_bf16 v[8:11], v[104:107], v[198:201], v[8:11]
	v_mfma_f32_16x16x32_bf16 v[60:63], v[84:87], v[164:167], v[60:63]
	v_mfma_f32_16x16x32_bf16 v[56:59], v[108:111], v[164:167], v[56:59]
	v_mfma_f32_16x16x32_bf16 v[44:47], v[84:87], v[172:175], v[44:47]
	v_mfma_f32_16x16x32_bf16 v[40:43], v[108:111], v[172:175], v[40:43]
	v_mfma_f32_16x16x32_bf16 v[28:31], v[84:87], v[180:183], v[28:31]
	v_mfma_f32_16x16x32_bf16 v[24:27], v[108:111], v[180:183], v[24:27]
	v_mfma_f32_16x16x32_bf16 v[12:15], v[84:87], v[202:205], v[12:15]
	v_mfma_f32_16x16x32_bf16 v[8:11], v[108:111], v[202:205], v[8:11]
	v_mfma_f32_16x16x32_bf16 v[52:55], v[128:131], v[160:163], v[52:55]
	v_mfma_f32_16x16x32_bf16 v[48:51], v[152:155], v[160:163], v[48:51]
	v_mfma_f32_16x16x32_bf16 v[36:39], v[128:131], v[168:171], v[36:39]
	v_mfma_f32_16x16x32_bf16 v[32:35], v[152:155], v[168:171], v[32:35]
	v_mfma_f32_16x16x32_bf16 v[20:23], v[128:131], v[176:179], v[20:23]
	v_mfma_f32_16x16x32_bf16 v[16:19], v[152:155], v[176:179], v[16:19]
	v_mfma_f32_16x16x32_bf16 v[4:7], v[128:131], v[198:201], v[4:7]
	v_mfma_f32_16x16x32_bf16 v[0:3], v[152:155], v[198:201], v[0:3]
	v_mfma_f32_16x16x32_bf16 v[52:55], v[136:139], v[164:167], v[52:55]
	v_mfma_f32_16x16x32_bf16 v[48:51], v[156:159], v[164:167], v[48:51]
	v_mfma_f32_16x16x32_bf16 v[36:39], v[136:139], v[172:175], v[36:39]
	v_mfma_f32_16x16x32_bf16 v[32:35], v[156:159], v[172:175], v[32:35]
	v_mfma_f32_16x16x32_bf16 v[20:23], v[136:139], v[180:183], v[20:23]
	v_mfma_f32_16x16x32_bf16 v[16:19], v[156:159], v[180:183], v[16:19]
	v_mfma_f32_16x16x32_bf16 v[4:7], v[136:139], v[202:205], v[4:7]
	v_mfma_f32_16x16x32_bf16 v[0:3], v[156:159], v[202:205], v[0:3]
	s_barrier
	s_add_u32 s16, s16, 0x10000
	s_addc_u32 s17, s17, 0
	s_add_u32 s66, s66, 0x10000
	s_addc_u32 s67, s67, 0
	s_cmp_ge_u32 s75, s53
	s_mov_b32 s18, s75

; #define PG8_STAGE(bufoff, gbase, voff) do { _Pragma("unroll") for (int _i = 0; _i < 2; ++_i) \
;         __builtin_amdgcn_global_load_lds((const unsigned*)((const char*)(gbase) + (voff)[_i]), (PG8_LAS unsigned*)(lds + (bufoff) + ldsw + _i * 8192), 16, 0, 0); } while (0)
; #define PG8_LDA(dst, b, h) do { _Pragma("unroll") for (int m = 0; m < 4; ++m) _Pragma("unroll") for (int k = 0; k < 2; ++k) dst[m][k] = *(const PG8_LAS bf16x8*)(lds + PG8_SA(b, h) + aoff + m * 2048 + k * 1024); } while (0)
; #define PG8_LDB(dst, b, h) do { _Pragma("unroll") for (int n = 0; n < 2; ++n) _Pragma("unroll") for (int k = 0; k < 2; ++k) dst[n][k] = *(const PG8_LAS bf16x8*)(lds + PG8_SB(b, h) + boff + n * 2048 + k * 1024); } while (0)
; #define PG8_MMA(ai, bj, At, Bt) do { __builtin_amdgcn_s_setprio(1); _Pragma("unroll") for (int m = 0; m < 4; ++m) _Pragma("unroll") for (int n = 0; n < 2; ++n) _Pragma("unroll") for (int k = 0; k < 2; ++k) \
;         acc[ai][bj][m][n] = __builtin_amdgcn_mfma_f32_16x16x32_bf16(Bt[n][k], At[m][k], acc[ai][bj][m][n], 0, 0, 0); __builtin_amdgcn_s_setprio(0); } while (0)
; #define PG8_WAIT_V(n) asm volatile("s_waitcnt vmcnt(" #n ")" ::: "memory")
; #define PG8_WAIT_L(n) asm volatile("s_waitcnt lgkmcnt(" #n ")" ::: "memory")
; #define PG8_BAR __builtin_amdgcn_s_barrier()
; #define PG8_SCHED __builtin_amdgcn_sched_barrier(0)
; template <class Epi, class Sched, bool ALIGN_EPI = false, bool SP2 = false>
; __device__ __forceinline__ void gemm_phase(PG8_LAS unsigned char* lds, const Gemm g, const Sched& S, const Epi& E) {
;     ...
;         const char* nA = has_next ? (const char*)g.A + (size_t)nxt.pm * tstep : cA; const char* nB = has_next ? (const char*)g.Bt + (size_t)nxt.pn * tstep : cB;
;         for (int t = 0; t < nt; t += 2) {
;             const bool last = (t == nt - 2);
;             const char* a1 = cA + (size_t)(t + 1) * kstep;
;             const char* a2 = last ? nA : cA + (size_t)(t + 2) * kstep; const char* b2 = last ? nB : cB + (size_t)(t + 2) * kstep;
;     ...
;             PG8_LDB(B0, 0, 0); PG8_LDB(B1, 0, 1); PG8_SCHED; PG8_LDA(At, 0, 0); PG8_STAGE(PG8_SA(1, 1), a1 + hstep, voffA);
;             PG8_WAIT_V(8); PG8_WAIT_L(0); PG8_BAR; PG8_MMA(0, 0, At, B0); PG8_MMA(0, 1, At, B1); PG8_BAR; PG8_SCHED;
;             PG8_LDA(At, 0, 1); PG8_STAGE(PG8_SB(0, 0), b2, voffB); PG8_STAGE(PG8_SB(0, 1), b2 + hstep, voffB); PG8_STAGE(PG8_SA(0, 0), a2, voffA);
.LBB0_1355:
	s_ashr_i32 s11, s10, 31
	s_lshl_b64 s[12:13], s[10:11], 19
	s_add_u32 s12, s22, s12
	s_addc_u32 s13, s23, s13
	s_and_b64 s[14:15], s[2:3], exec
	s_cselect_b32 s11, s13, s19
	s_cselect_b32 s40, s12, s18
	s_ashr_i32 s9, s8, 31
	s_lshl_b64 s[14:15], s[8:9], 19
	s_add_u32 s14, s27, s14
	s_addc_u32 s15, s28, s15
	s_and_b64 s[62:63], s[2:3], exec
	s_cselect_b32 s9, s15, s21
	s_cselect_b32 s61, s14, s20
	s_add_u32 s18, s18, 0xc000
	s_addc_u32 s19, s19, 0
	s_add_u32 s66, s20, 0x10000
	v_mov_b32_e32 v0, 0
	s_addc_u32 s67, s21, 0
	s_mov_b32 s68, -2
	v_add_u32_e32 v246, 0x10000, v162
	s_add_u32 s20, s18, 0x4000
	s_addc_u32 s21, s19, 0
	s_cmp_eq_u32 s68, 12
	s_cselect_b32 s64, s40, s20
	s_cselect_b32 s65, s11, s21
	s_cselect_b32 s62, s61, s66
	s_cselect_b32 s63, s9, s67
	s_add_u32 s20, s64, 0x8000
	s_addc_u32 s21, s65, 0
	s_add_i32 s69, 0, 0x10000
	s_add_i32 s72, 0, 0x14000
	ds_read_b128 v[128:131], v246
	ds_read_b128 v[132:135], v246 offset:1024
	ds_read_b128 v[136:139], v246 offset:2048
	ds_read_b128 v[140:143], v246 offset:3072
	ds_read_b128 v[156:159], v246 offset:16384
	ds_read_b128 v[164:167], v246 offset:17408
	ds_read_b128 v[168:171], v246 offset:18432
	ds_read_b128 v[172:175], v246 offset:19456
	s_add_i32 m0, s37, 0xc000
	ds_read_b128 v[176:179], v163
	ds_read_b128 v[180:183], v163 offset:1024
	ds_read_b128 v[184:187], v163 offset:2048
	ds_read_b128 v[188:191], v163 offset:3072
	ds_read_b128 v[192:195], v163 offset:4096
	ds_read_b128 v[196:199], v163 offset:5120
	ds_read_b128 v[200:203], v163 offset:6144
	ds_read_b128 v[204:207], v163 offset:7168
	global_load_lds_dwordx4 v152, s[18:19]
	s_add_i32 m0, s37, 0xe000
	s_nop 0
	global_load_lds_dwordx4 v154, s[18:19]
	s_waitcnt vmcnt(8) lgkmcnt(0)
	s_barrier
	v_mfma_f32_16x16x32_bf16 v[124:127], v[128:131], v[176:179], 0
	v_mfma_f32_16x16x32_bf16 v[120:123], v[136:139], v[176:179], 0
	v_mfma_f32_16x16x32_bf16 v[108:111], v[128:131], v[184:187], 0
	v_mfma_f32_16x16x32_bf16 v[104:107], v[136:139], v[184:187], 0
	v_mfma_f32_16x16x32_bf16 v[92:95], v[128:131], v[192:195], 0
	v_mfma_f32_16x16x32_bf16 v[88:91], v[136:139], v[192:195], 0
	v_mfma_f32_16x16x32_bf16 v[76:79], v[128:131], v[200:203], 0
	v_mfma_f32_16x16x32_bf16 v[72:75], v[136:139], v[200:203], 0
	v_mfma_f32_16x16x32_bf16 v[124:127], v[132:135], v[180:183], v[124:127]
	v_mfma_f32_16x16x32_bf16 v[120:123], v[140:143], v[180:183], v[120:123]
	v_mfma_f32_16x16x32_bf16 v[108:111], v[132:135], v[188:191], v[108:111]
	v_mfma_f32_16x16x32_bf16 v[104:107], v[140:143], v[188:191], v[104:107]
	v_mfma_f32_16x16x32_bf16 v[92:95], v[132:135], v[196:199], v[92:95]
	v_mfma_f32_16x16x32_bf16 v[88:91], v[140:143], v[196:199], v[88:91]
	v_mfma_f32_16x16x32_bf16 v[76:79], v[132:135], v[204:207], v[76:79]
	v_mfma_f32_16x16x32_bf16 v[72:75], v[140:143], v[204:207], v[72:75]
	v_mfma_f32_16x16x32_bf16 v[116:119], v[156:159], v[176:179], 0
	v_mfma_f32_16x16x32_bf16 v[112:115], v[168:171], v[176:179], 0
	v_mfma_f32_16x16x32_bf16 v[100:103], v[156:159], v[184:187], 0
	v_mfma_f32_16x16x32_bf16 v[96:99], v[168:171], v[184:187], 0
	v_mfma_f32_16x16x32_bf16 v[84:87], v[156:159], v[192:195], 0
	v_mfma_f32_16x16x32_bf16 v[80:83], v[168:171], v[192:195], 0
	v_mfma_f32_16x16x32_bf16 v[68:71], v[156:159], v[200:203], 0
	v_mfma_f32_16x16x32_bf16 v[64:67], v[168:171], v[200:203], 0
	v_mfma_f32_16x16x32_bf16 v[116:119], v[164:167], v[180:183], v[116:119]
	v_mfma_f32_16x16x32_bf16 v[112:115], v[172:175], v[180:183], v[112:115]
	v_mfma_f32_16x16x32_bf16 v[100:103], v[164:167], v[188:191], v[100:103]
	v_mfma_f32_16x16x32_bf16 v[96:99], v[172:175], v[188:191], v[96:99]
	v_mfma_f32_16x16x32_bf16 v[84:87], v[164:167], v[196:199], v[84:87]
	v_mfma_f32_16x16x32_bf16 v[80:83], v[172:175], v[196:199], v[80:83]
	v_mfma_f32_16x16x32_bf16 v[68:71], v[164:167], v[204:207], v[68:71]
	v_mfma_f32_16x16x32_bf16 v[64:67], v[172:175], v[204:207], v[64:67]
	s_barrier
	s_add_i32 s69, s69, s30
	s_mov_b32 m0, s69
	ds_read_b128 v[176:179], v163 offset:16384
	ds_read_b128 v[180:183], v163 offset:17408
	ds_read_b128 v[184:187], v163 offset:18432
	ds_read_b128 v[188:191], v163 offset:19456
	ds_read_b128 v[192:195], v163 offset:20480
	ds_read_b128 v[196:199], v163 offset:21504
	ds_read_b128 v[200:203], v163 offset:22528
	ds_read_b128 v[204:207], v163 offset:23552
	global_load_lds_dwordx4 v148, s[62:63]
	s_add_i32 m0, s69, 0x2000
	s_add_u32 s70, s62, 0x4000
	s_addc_u32 s71, s63, 0
	s_add_i32 s69, s72, s30
	global_load_lds_dwordx4 v144, s[62:63]
	s_mov_b32 m0, s69
	s_nop 0
	global_load_lds_dwordx4 v148, s[70:71]
	s_add_i32 m0, s69, 0x2000
	s_nop 0
	global_load_lds_dwordx4 v144, s[70:71]
	s_mov_b32 m0, s37
	s_nop 0
	global_load_lds_dwordx4 v150, s[64:65]
	s_mov_b32 m0, s39
	s_nop 0
	global_load_lds_dwordx4 v146, s[64:65]
	s_waitcnt vmcnt(8) lgkmcnt(0)
	s_barrier
; #define PG8_STAGE(bufoff, gbase, voff) do { _Pragma("unroll") for (int _i = 0; _i < 2; ++_i) \
;         __builtin_amdgcn_global_load_lds((const unsigned*)((const char*)(gbase) + (voff)[_i]), (PG8_LAS unsigned*)(lds + (bufoff) + ldsw + _i * 8192), 16, 0, 0); } while (0)
; #define PG8_LDA(dst, b, h) do { _Pragma("unroll") for (int m = 0; m < 4; ++m) _Pragma("unroll") for (int k = 0; k < 2; ++k) dst[m][k] = *(const PG8_LAS bf16x8*)(lds + PG8_SA(b, h) + aoff + m * 2048 + k * 1024); } while (0)
; #define PG8_LDB(dst, b, h) do { _Pragma("unroll") for (int n = 0; n < 2; ++n) _Pragma("unroll") for (int k = 0; k < 2; ++k) dst[n][k] = *(const PG8_LAS bf16x8*)(lds + PG8_SB(b, h) + boff + n * 2048 + k * 1024); } while (0)
; #define PG8_MMA(ai, bj, At, Bt) do { __builtin_amdgcn_s_setprio(1); _Pragma("unroll") for (int m = 0; m < 4; ++m) _Pragma("unroll") for (int n = 0; n < 2; ++n) _Pragma("unroll") for (int k = 0; k < 2; ++k) \
;         acc[ai][bj][m][n] = __builtin_amdgcn_mfma_f32_16x16x32_bf16(Bt[n][k], At[m][k], acc[ai][bj][m][n], 0, 0, 0); __builtin_amdgcn_s_setprio(0); } while (0)
; #define PG8_WAIT_V(n) asm volatile("s_waitcnt vmcnt(" #n ")" ::: "memory")
; #define PG8_WAIT_L(n) asm volatile("s_waitcnt lgkmcnt(" #n ")" ::: "memory")
; #define PG8_BAR __builtin_amdgcn_s_barrier()
; #define PG8_SCHED __builtin_amdgcn_sched_barrier(0)
; template <class Epi, class Sched, bool ALIGN_EPI = false, bool SP2 = false>
; __device__ __forceinline__ void gemm_phase(PG8_LAS unsigned char* lds, const Gemm g, const Sched& S, const Epi& E) {
;     ...
;             PG8_WAIT_V(8); PG8_WAIT_L(0); PG8_BAR; PG8_MMA(1, 0, At, B0); PG8_MMA(1, 1, At, B1); PG8_BAR; PG8_SCHED;
;             PG8_LDB(B0, 1, 0); PG8_LDB(B1, 1, 1); PG8_SCHED; PG8_LDA(At, 1, 0); PG8_STAGE(PG8_SA(0, 1), a2 + hstep, voffA);
;             PG8_WAIT_V(8); PG8_WAIT_L(0); PG8_BAR; PG8_MMA(0, 0, At, B0); PG8_MMA(0, 1, At, B1); PG8_BAR; PG8_SCHED;
	v_mfma_f32_16x16x32_bf16 v[60:63], v[128:131], v[176:179], 0
	v_mfma_f32_16x16x32_bf16 v[56:59], v[136:139], v[176:179], 0
	v_mfma_f32_16x16x32_bf16 v[44:47], v[128:131], v[184:187], 0
	v_mfma_f32_16x16x32_bf16 v[40:43], v[136:139], v[184:187], 0
	v_mfma_f32_16x16x32_bf16 v[28:31], v[128:131], v[192:195], 0
	v_mfma_f32_16x16x32_bf16 v[24:27], v[136:139], v[192:195], 0
	v_mfma_f32_16x16x32_bf16 v[12:15], v[128:131], v[200:203], 0
	v_mfma_f32_16x16x32_bf16 v[8:11], v[136:139], v[200:203], 0
	v_mfma_f32_16x16x32_bf16 v[60:63], v[132:135], v[180:183], v[60:63]
	v_mfma_f32_16x16x32_bf16 v[56:59], v[140:143], v[180:183], v[56:59]
	v_mfma_f32_16x16x32_bf16 v[44:47], v[132:135], v[188:191], v[44:47]
	v_mfma_f32_16x16x32_bf16 v[40:43], v[140:143], v[188:191], v[40:43]
	v_mfma_f32_16x16x32_bf16 v[28:31], v[132:135], v[196:199], v[28:31]
	v_mfma_f32_16x16x32_bf16 v[24:27], v[140:143], v[196:199], v[24:27]
	v_mfma_f32_16x16x32_bf16 v[12:15], v[132:135], v[204:207], v[12:15]
	v_mfma_f32_16x16x32_bf16 v[8:11], v[140:143], v[204:207], v[8:11]
	v_mfma_f32_16x16x32_bf16 v[52:55], v[156:159], v[176:179], 0
	v_mfma_f32_16x16x32_bf16 v[48:51], v[168:171], v[176:179], 0
	v_mfma_f32_16x16x32_bf16 v[36:39], v[156:159], v[184:187], 0
	v_mfma_f32_16x16x32_bf16 v[32:35], v[168:171], v[184:187], 0
	v_mfma_f32_16x16x32_bf16 v[20:23], v[156:159], v[192:195], 0
	v_mfma_f32_16x16x32_bf16 v[16:19], v[168:171], v[192:195], 0
	v_mfma_f32_16x16x32_bf16 v[4:7], v[156:159], v[200:203], 0
	v_mfma_f32_16x16x32_bf16 v[0:3], v[168:171], v[200:203], 0
	v_mfma_f32_16x16x32_bf16 v[52:55], v[164:167], v[180:183], v[52:55]
	v_mfma_f32_16x16x32_bf16 v[48:51], v[172:175], v[180:183], v[48:51]
	v_mfma_f32_16x16x32_bf16 v[36:39], v[164:167], v[188:191], v[36:39]
	v_mfma_f32_16x16x32_bf16 v[32:35], v[172:175], v[188:191], v[32:35]
	v_mfma_f32_16x16x32_bf16 v[20:23], v[164:167], v[196:199], v[20:23]
	v_mfma_f32_16x16x32_bf16 v[16:19], v[172:175], v[196:199], v[16:19]
	v_mfma_f32_16x16x32_bf16 v[4:7], v[164:167], v[204:207], v[4:7]
	v_mfma_f32_16x16x32_bf16 v[0:3], v[172:175], v[204:207], v[0:3]
	s_barrier
	s_add_i32 s69, 0, 0x18000
	s_add_i32 s70, 0, 0x1c000
	ds_read_b128 v[128:131], v246 offset:32768
	ds_read_b128 v[132:135], v246 offset:33792
	ds_read_b128 v[136:139], v246 offset:34816
	ds_read_b128 v[140:143], v246 offset:35840
	ds_read_b128 v[156:159], v246 offset:49152
	ds_read_b128 v[164:167], v246 offset:50176
	ds_read_b128 v[168:171], v246 offset:51200
	ds_read_b128 v[172:175], v246 offset:52224
	s_add_u32 s64, s64, 0x4000
	s_addc_u32 s65, s65, 0
	s_mov_b32 m0, s41
	ds_read_b128 v[176:179], v163 offset:32768
	ds_read_b128 v[180:183], v163 offset:33792
	ds_read_b128 v[184:187], v163 offset:34816
	ds_read_b128 v[188:191], v163 offset:35840
	ds_read_b128 v[192:195], v163 offset:36864
	ds_read_b128 v[196:199], v163 offset:37888
	ds_read_b128 v[200:203], v163 offset:38912
	ds_read_b128 v[204:207], v163 offset:39936
	global_load_lds_dwordx4 v150, s[64:65]
	s_mov_b32 m0, s42
	s_nop 0
	global_load_lds_dwordx4 v146, s[64:65]
	s_waitcnt vmcnt(8) lgkmcnt(0)
	s_barrier
	v_mfma_f32_16x16x32_bf16 v[124:127], v[128:131], v[176:179], v[124:127]
	v_mfma_f32_16x16x32_bf16 v[120:123], v[136:139], v[176:179], v[120:123]
	v_mfma_f32_16x16x32_bf16 v[108:111], v[128:131], v[184:187], v[108:111]
	v_mfma_f32_16x16x32_bf16 v[104:107], v[136:139], v[184:187], v[104:107]
	v_mfma_f32_16x16x32_bf16 v[92:95], v[128:131], v[192:195], v[92:95]
	v_mfma_f32_16x16x32_bf16 v[88:91], v[136:139], v[192:195], v[88:91]
	v_mfma_f32_16x16x32_bf16 v[76:79], v[128:131], v[200:203], v[76:79]
	v_mfma_f32_16x16x32_bf16 v[72:75], v[136:139], v[200:203], v[72:75]
	v_mfma_f32_16x16x32_bf16 v[124:127], v[132:135], v[180:183], v[124:127]
	v_mfma_f32_16x16x32_bf16 v[120:123], v[140:143], v[180:183], v[120:123]
	v_mfma_f32_16x16x32_bf16 v[108:111], v[132:135], v[188:191], v[108:111]
	v_mfma_f32_16x16x32_bf16 v[104:107], v[140:143], v[188:191], v[104:107]
	v_mfma_f32_16x16x32_bf16 v[92:95], v[132:135], v[196:199], v[92:95]
	v_mfma_f32_16x16x32_bf16 v[88:91], v[140:143], v[196:199], v[88:91]
	v_mfma_f32_16x16x32_bf16 v[76:79], v[132:135], v[204:207], v[76:79]
	v_mfma_f32_16x16x32_bf16 v[72:75], v[140:143], v[204:207], v[72:75]
	v_mfma_f32_16x16x32_bf16 v[116:119], v[156:159], v[176:179], v[116:119]
	v_mfma_f32_16x16x32_bf16 v[112:115], v[168:171], v[176:179], v[112:115]
	v_mfma_f32_16x16x32_bf16 v[100:103], v[156:159], v[184:187], v[100:103]
	v_mfma_f32_16x16x32_bf16 v[96:99], v[168:171], v[184:187], v[96:99]
	v_mfma_f32_16x16x32_bf16 v[84:87], v[156:159], v[192:195], v[84:87]
	v_mfma_f32_16x16x32_bf16 v[80:83], v[168:171], v[192:195], v[80:83]
	v_mfma_f32_16x16x32_bf16 v[68:71], v[156:159], v[200:203], v[68:71]
	v_mfma_f32_16x16x32_bf16 v[64:67], v[168:171], v[200:203], v[64:67]
	v_mfma_f32_16x16x32_bf16 v[116:119], v[164:167], v[180:183], v[116:119]
	v_mfma_f32_16x16x32_bf16 v[112:115], v[172:175], v[180:183], v[112:115]
	v_mfma_f32_16x16x32_bf16 v[100:103], v[164:167], v[188:191], v[100:103]
	v_mfma_f32_16x16x32_bf16 v[96:99], v[172:175], v[188:191], v[96:99]
	v_mfma_f32_16x16x32_bf16 v[84:87], v[164:167], v[196:199], v[84:87]
	v_mfma_f32_16x16x32_bf16 v[80:83], v[172:175], v[196:199], v[80:83]
	v_mfma_f32_16x16x32_bf16 v[68:71], v[164:167], v[204:207], v[68:71]
	v_mfma_f32_16x16x32_bf16 v[64:67], v[172:175], v[204:207], v[64:67]
	s_barrier
; #define PG8_STAGE(bufoff, gbase, voff) do { _Pragma("unroll") for (int _i = 0; _i < 2; ++_i) \
;         __builtin_amdgcn_global_load_lds((const unsigned*)((const char*)(gbase) + (voff)[_i]), (PG8_LAS unsigned*)(lds + (bufoff) + ldsw + _i * 8192), 16, 0, 0); } while (0)
; #define PG8_LDA(dst, b, h) do { _Pragma("unroll") for (int m = 0; m < 4; ++m) _Pragma("unroll") for (int k = 0; k < 2; ++k) dst[m][k] = *(const PG8_LAS bf16x8*)(lds + PG8_SA(b, h) + aoff + m * 2048 + k * 1024); } while (0)
; #define PG8_MMA(ai, bj, At, Bt) do { __builtin_amdgcn_s_setprio(1); _Pragma("unroll") for (int m = 0; m < 4; ++m) _Pragma("unroll") for (int n = 0; n < 2; ++n) _Pragma("unroll") for (int k = 0; k < 2; ++k) \
;         acc[ai][bj][m][n] = __builtin_amdgcn_mfma_f32_16x16x32_bf16(Bt[n][k], At[m][k], acc[ai][bj][m][n], 0, 0, 0); __builtin_amdgcn_s_setprio(0); } while (0)
; #define PG8_WAIT_V(n) asm volatile("s_waitcnt vmcnt(" #n ")" ::: "memory")
; #define PG8_WAIT_L(n) asm volatile("s_waitcnt lgkmcnt(" #n ")" ::: "memory")
; #define PG8_BAR __builtin_amdgcn_s_barrier()
; #define PG8_SCHED __builtin_amdgcn_sched_barrier(0)
; template <class Epi, class Sched, bool ALIGN_EPI = false, bool SP2 = false>
; __device__ __forceinline__ void gemm_phase(PG8_LAS unsigned char* lds, const Gemm g, const Sched& S, const Epi& E) {
;     ...
;             PG8_LDA(At, 1, 1); PG8_STAGE(PG8_SB(1, 0), b3, voffB); PG8_STAGE(PG8_SB(1, 1), b3 + hstep, voffB); PG8_STAGE(PG8_SA(1, 0), a3, voffA);
;             PG8_WAIT_V(8); PG8_WAIT_L(0); PG8_BAR; PG8_MMA(1, 0, At, B0); PG8_MMA(1, 1, At, B1); PG8_BAR; PG8_SCHED;
	s_add_u32 s64, s62, 0x8000
	s_addc_u32 s65, s63, 0
	s_add_i32 s69, s69, s30
	s_mov_b32 m0, s69
	ds_read_b128 v[176:179], v163 offset:49152
	ds_read_b128 v[180:183], v163 offset:50176
	ds_read_b128 v[184:187], v163 offset:51200
	ds_read_b128 v[188:191], v163 offset:52224
	ds_read_b128 v[192:195], v163 offset:53248
	ds_read_b128 v[196:199], v163 offset:54272
	ds_read_b128 v[200:203], v163 offset:55296
	ds_read_b128 v[204:207], v163 offset:56320
	global_load_lds_dwordx4 v148, s[64:65]
	s_add_i32 m0, s69, 0x2000
	s_add_u32 s62, s62, 0xc000
	s_addc_u32 s63, s63, 0
	s_add_i32 s91, s70, s30
	global_load_lds_dwordx4 v144, s[64:65]
	s_mov_b32 m0, s91
	s_nop 0
	global_load_lds_dwordx4 v148, s[62:63]
	s_add_i32 m0, s91, 0x2000
	s_nop 0
	global_load_lds_dwordx4 v144, s[62:63]
	s_mov_b32 m0, s54
	s_nop 0
	global_load_lds_dwordx4 v150, s[20:21]
	s_mov_b32 m0, s55
	s_nop 0
	global_load_lds_dwordx4 v146, s[20:21]
	s_waitcnt vmcnt(8) lgkmcnt(0)
	s_barrier
	v_mfma_f32_16x16x32_bf16 v[60:63], v[128:131], v[176:179], v[60:63]
	v_mfma_f32_16x16x32_bf16 v[56:59], v[136:139], v[176:179], v[56:59]
	v_mfma_f32_16x16x32_bf16 v[44:47], v[128:131], v[184:187], v[44:47]
	v_mfma_f32_16x16x32_bf16 v[40:43], v[136:139], v[184:187], v[40:43]
	v_mfma_f32_16x16x32_bf16 v[28:31], v[128:131], v[192:195], v[28:31]
	v_mfma_f32_16x16x32_bf16 v[24:27], v[136:139], v[192:195], v[24:27]
	v_mfma_f32_16x16x32_bf16 v[12:15], v[128:131], v[200:203], v[12:15]
	v_mfma_f32_16x16x32_bf16 v[8:11], v[136:139], v[200:203], v[8:11]
	v_mfma_f32_16x16x32_bf16 v[60:63], v[132:135], v[180:183], v[60:63]
	v_mfma_f32_16x16x32_bf16 v[56:59], v[140:143], v[180:183], v[56:59]
	v_mfma_f32_16x16x32_bf16 v[44:47], v[132:135], v[188:191], v[44:47]
	v_mfma_f32_16x16x32_bf16 v[40:43], v[140:143], v[188:191], v[40:43]
	v_mfma_f32_16x16x32_bf16 v[28:31], v[132:135], v[196:199], v[28:31]
	v_mfma_f32_16x16x32_bf16 v[24:27], v[140:143], v[196:199], v[24:27]
	v_mfma_f32_16x16x32_bf16 v[12:15], v[132:135], v[204:207], v[12:15]
	v_mfma_f32_16x16x32_bf16 v[8:11], v[140:143], v[204:207], v[8:11]
	v_mfma_f32_16x16x32_bf16 v[52:55], v[156:159], v[176:179], v[52:55]
	v_mfma_f32_16x16x32_bf16 v[48:51], v[168:171], v[176:179], v[48:51]
	v_mfma_f32_16x16x32_bf16 v[36:39], v[156:159], v[184:187], v[36:39]
	v_mfma_f32_16x16x32_bf16 v[32:35], v[168:171], v[184:187], v[32:35]
	v_mfma_f32_16x16x32_bf16 v[20:23], v[156:159], v[192:195], v[20:23]
	v_mfma_f32_16x16x32_bf16 v[16:19], v[168:171], v[192:195], v[16:19]
	v_mfma_f32_16x16x32_bf16 v[4:7], v[156:159], v[200:203], v[4:7]
	v_mfma_f32_16x16x32_bf16 v[0:3], v[168:171], v[200:203], v[0:3]
	v_mfma_f32_16x16x32_bf16 v[52:55], v[164:167], v[180:183], v[52:55]
	v_mfma_f32_16x16x32_bf16 v[48:51], v[172:175], v[180:183], v[48:51]
	v_mfma_f32_16x16x32_bf16 v[36:39], v[164:167], v[188:191], v[36:39]
	v_mfma_f32_16x16x32_bf16 v[32:35], v[172:175], v[188:191], v[32:35]
	v_mfma_f32_16x16x32_bf16 v[20:23], v[164:167], v[196:199], v[20:23]
	v_mfma_f32_16x16x32_bf16 v[16:19], v[172:175], v[196:199], v[16:19]
	v_mfma_f32_16x16x32_bf16 v[4:7], v[164:167], v[204:207], v[4:7]
	v_mfma_f32_16x16x32_bf16 v[0:3], v[172:175], v[204:207], v[0:3]
	s_barrier
	s_add_i32 s68, s68, 2
	s_add_u32 s18, s18, 0x10000
	s_addc_u32 s19, s19, 0
	s_add_u32 s66, s66, 0x10000
	s_addc_u32 s67, s67, 0
	s_cmp_gt_u32 s68, 13
